# GEMM K-loop: each load segment's LDS-DMA issue moved into the following MFMA run (interleaved, m0 hazard covered by an MFMA); segment waits become vmcnt(8-n) so the completed set at every barrier is u
# speedup vs baseline: 1.0006x; 1.0006x over previous
.LBB0_246:
	s_andn2_b64 vcc, exec, s[18:19]
	s_cbranch_vccnz .Lk_zero_skip
	v_add_u32_e32 v236, 0x10000, v227
	v_add_u32_e32 v237, 0x14000, v227
	v_add_u32_e32 v238, 0x18000, v227
	v_add_u32_e32 v239, 0x1c000, v227
	s_add_u32 s44, s44, 0x80
	s_addc_u32 s45, s45, 0
	s_add_u32 s23, s46, 0x100
	s_addc_u32 s48, s47, 0
	s_mov_b32 s46, 0
	s_add_i32 s49, s46, 2
	s_add_u32 s69, s44, 0x80
	s_addc_u32 s47, s45, 0
	s_add_i32 s80, 0, 0x10000
	s_cmp_eq_u32 s90, s46
	s_cselect_b32 s47, s65, s47
	s_cselect_b32 s46, s64, s69
	s_cselect_b32 s71, s67, s48
	s_cselect_b32 s70, s66, s23
	s_add_i32 s69, 0, 0x14000
	ds_read_b128 v[128:131], v236
	ds_read_b128 v[132:135], v236 offset:1024
	ds_read_b128 v[136:139], v236 offset:2048
	ds_read_b128 v[140:143], v236 offset:3072
	ds_read_b128 v[144:147], v237
	ds_read_b128 v[148:151], v237 offset:1024
	ds_read_b128 v[174:177], v237 offset:2048
	ds_read_b128 v[178:181], v237 offset:3072
	ds_read_b128 v[182:185], v230
	ds_read_b128 v[186:189], v230 offset:1024
	ds_read_b128 v[190:193], v230 offset:2048
	ds_read_b128 v[194:197], v230 offset:3072
	ds_read_b128 v[198:201], v230 offset:4096
	ds_read_b128 v[202:205], v230 offset:5120
	ds_read_b128 v[206:209], v230 offset:6144
	ds_read_b128 v[232:235], v230 offset:7168
	s_waitcnt vmcnt(6)
	s_waitcnt lgkmcnt(0)
	s_barrier
	s_setprio 1
	s_waitcnt lgkmcnt(0)
	v_mfma_f32_16x16x32_bf16 v[16:19], v[128:131], v[182:185], 0
	v_mfma_f32_16x16x32_bf16 v[28:31], v[136:139], v[182:185], 0
	v_mfma_f32_16x16x32_bf16 v[12:15], v[128:131], v[190:193], 0
	v_mfma_f32_16x16x32_bf16 v[8:11], v[136:139], v[190:193], 0
	v_mfma_f32_16x16x32_bf16 v[124:127], v[128:131], v[198:201], 0
	v_mfma_f32_16x16x32_bf16 v[120:123], v[136:139], v[198:201], 0
	v_mfma_f32_16x16x32_bf16 v[108:111], v[128:131], v[206:209], 0
	v_mfma_f32_16x16x32_bf16 v[104:107], v[136:139], v[206:209], 0
	s_add_i32 m0, s50, 0xc000
	v_mfma_f32_16x16x32_bf16 v[16:19], v[132:135], v[186:189], v[16:19]
	global_load_lds_dwordx4 v170, s[44:45]
	v_mfma_f32_16x16x32_bf16 v[28:31], v[140:143], v[186:189], v[28:31]
	v_mfma_f32_16x16x32_bf16 v[12:15], v[132:135], v[194:197], v[12:15]
	v_mfma_f32_16x16x32_bf16 v[8:11], v[140:143], v[194:197], v[8:11]
	v_mfma_f32_16x16x32_bf16 v[124:127], v[132:135], v[202:205], v[124:127]
	v_mfma_f32_16x16x32_bf16 v[120:123], v[140:143], v[202:205], v[120:123]
	v_mfma_f32_16x16x32_bf16 v[108:111], v[132:135], v[232:235], v[108:111]
	v_mfma_f32_16x16x32_bf16 v[104:107], v[140:143], v[232:235], v[104:107]
	s_setprio 0
	s_setprio 1
	v_mfma_f32_16x16x32_bf16 v[24:27], v[144:147], v[182:185], 0
	v_mfma_f32_16x16x32_bf16 v[20:23], v[174:177], v[182:185], 0
	v_mfma_f32_16x16x32_bf16 v[4:7], v[144:147], v[190:193], 0
	v_mfma_f32_16x16x32_bf16 v[0:3], v[174:177], v[190:193], 0
	v_mfma_f32_16x16x32_bf16 v[116:119], v[144:147], v[198:201], 0
	v_mfma_f32_16x16x32_bf16 v[112:115], v[174:177], v[198:201], 0
	v_mfma_f32_16x16x32_bf16 v[100:103], v[144:147], v[206:209], 0
	v_mfma_f32_16x16x32_bf16 v[96:99], v[174:177], v[206:209], 0
	s_add_i32 m0, s50, 0xe000
	v_mfma_f32_16x16x32_bf16 v[24:27], v[148:151], v[186:189], v[24:27]
	global_load_lds_dwordx4 v172, s[44:45]
	v_mfma_f32_16x16x32_bf16 v[20:23], v[178:181], v[186:189], v[20:23]
	v_mfma_f32_16x16x32_bf16 v[4:7], v[148:151], v[194:197], v[4:7]
	v_mfma_f32_16x16x32_bf16 v[0:3], v[178:181], v[194:197], v[0:3]
	v_mfma_f32_16x16x32_bf16 v[116:119], v[148:151], v[202:205], v[116:119]
	v_mfma_f32_16x16x32_bf16 v[112:115], v[178:181], v[202:205], v[112:115]
	v_mfma_f32_16x16x32_bf16 v[100:103], v[148:151], v[232:235], v[100:103]
	v_mfma_f32_16x16x32_bf16 v[96:99], v[178:181], v[232:235], v[96:99]
	s_setprio 0
	s_barrier
	ds_read_b128 v[182:185], v230 offset:16384
	ds_read_b128 v[186:189], v230 offset:17408
	ds_read_b128 v[190:193], v230 offset:18432
	ds_read_b128 v[194:197], v230 offset:19456
	ds_read_b128 v[198:201], v230 offset:20480
	ds_read_b128 v[202:205], v230 offset:21504
	ds_read_b128 v[206:209], v230 offset:22528
	ds_read_b128 v[232:235], v230 offset:23552
	s_waitcnt vmcnt(2)
	s_waitcnt lgkmcnt(0)
	s_barrier
	s_setprio 1
	s_waitcnt lgkmcnt(0)
	v_mfma_f32_16x16x32_bf16 v[92:95], v[128:131], v[182:185], 0
	v_mfma_f32_16x16x32_bf16 v[88:91], v[136:139], v[182:185], 0
	s_add_i32 s80, s80, s3
	s_mov_b32 m0, s80
	v_mfma_f32_16x16x32_bf16 v[76:79], v[128:131], v[190:193], 0
	global_load_lds_dwordx4 v160, s[70:71]
	v_mfma_f32_16x16x32_bf16 v[72:75], v[136:139], v[190:193], 0
	v_mfma_f32_16x16x32_bf16 v[60:63], v[128:131], v[198:201], 0
	v_mfma_f32_16x16x32_bf16 v[56:59], v[136:139], v[198:201], 0
	v_mfma_f32_16x16x32_bf16 v[44:47], v[128:131], v[206:209], 0
	v_mfma_f32_16x16x32_bf16 v[40:43], v[136:139], v[206:209], 0
	s_add_i32 m0, s80, 0x2000
	s_add_i32 s69, s69, s3
	v_mfma_f32_16x16x32_bf16 v[92:95], v[132:135], v[186:189], v[92:95]
	global_load_lds_dwordx4 v164, s[70:71]
	v_mfma_f32_16x16x32_bf16 v[88:91], v[140:143], v[186:189], v[88:91]
	v_mfma_f32_16x16x32_bf16 v[76:79], v[132:135], v[194:197], v[76:79]
	v_mfma_f32_16x16x32_bf16 v[72:75], v[140:143], v[194:197], v[72:75]
	v_mfma_f32_16x16x32_bf16 v[60:63], v[132:135], v[202:205], v[60:63]
	s_add_u32 s70, s70, s26
	s_addc_u32 s71, s71, 0
	s_mov_b32 m0, s69
	v_mfma_f32_16x16x32_bf16 v[56:59], v[140:143], v[202:205], v[56:59]
	global_load_lds_dwordx4 v160, s[70:71]
	v_mfma_f32_16x16x32_bf16 v[44:47], v[132:135], v[232:235], v[44:47]
	v_mfma_f32_16x16x32_bf16 v[40:43], v[140:143], v[232:235], v[40:43]
	s_setprio 0
	s_setprio 1
	v_mfma_f32_16x16x32_bf16 v[84:87], v[144:147], v[182:185], 0
	v_mfma_f32_16x16x32_bf16 v[80:83], v[174:177], v[182:185], 0
	s_add_i32 m0, s69, 0x2000
	v_mfma_f32_16x16x32_bf16 v[68:71], v[144:147], v[190:193], 0
	global_load_lds_dwordx4 v164, s[70:71]
	v_mfma_f32_16x16x32_bf16 v[64:67], v[174:177], v[190:193], 0
	v_mfma_f32_16x16x32_bf16 v[52:55], v[144:147], v[198:201], 0
	v_mfma_f32_16x16x32_bf16 v[48:51], v[174:177], v[198:201], 0
	v_mfma_f32_16x16x32_bf16 v[36:39], v[144:147], v[206:209], 0
	v_mfma_f32_16x16x32_bf16 v[32:35], v[174:177], v[206:209], 0
	s_mov_b32 m0, s50
	v_mfma_f32_16x16x32_bf16 v[84:87], v[148:151], v[186:189], v[84:87]
	global_load_lds_dwordx4 v158, s[46:47]
	v_mfma_f32_16x16x32_bf16 v[80:83], v[178:181], v[186:189], v[80:83]
	v_mfma_f32_16x16x32_bf16 v[68:71], v[148:151], v[194:197], v[68:71]
	v_mfma_f32_16x16x32_bf16 v[64:67], v[178:181], v[194:197], v[64:67]
	v_mfma_f32_16x16x32_bf16 v[52:55], v[148:151], v[202:205], v[52:55]
	s_mov_b32 m0, s51
	v_mfma_f32_16x16x32_bf16 v[48:51], v[178:181], v[202:205], v[48:51]
	global_load_lds_dwordx4 v162, s[46:47]
	v_mfma_f32_16x16x32_bf16 v[36:39], v[148:151], v[232:235], v[36:39]
	v_mfma_f32_16x16x32_bf16 v[32:35], v[178:181], v[232:235], v[32:35]
	s_setprio 0
	s_barrier
	ds_read_b128 v[128:131], v238
	ds_read_b128 v[132:135], v238 offset:1024
	ds_read_b128 v[136:139], v238 offset:2048
	ds_read_b128 v[140:143], v238 offset:3072
	ds_read_b128 v[144:147], v239
	ds_read_b128 v[148:151], v239 offset:1024
	ds_read_b128 v[174:177], v239 offset:2048
	ds_read_b128 v[178:181], v239 offset:3072
	ds_read_b128 v[182:185], v230 offset:32768
	ds_read_b128 v[186:189], v230 offset:33792
	ds_read_b128 v[190:193], v230 offset:34816
	ds_read_b128 v[194:197], v230 offset:35840
	ds_read_b128 v[198:201], v230 offset:36864
	ds_read_b128 v[202:205], v230 offset:37888
	ds_read_b128 v[206:209], v230 offset:38912
	ds_read_b128 v[232:235], v230 offset:39936
	s_waitcnt vmcnt(6)
	s_waitcnt lgkmcnt(0)
	s_barrier
	s_setprio 1
	s_waitcnt lgkmcnt(0)
	v_mfma_f32_16x16x32_bf16 v[16:19], v[128:131], v[182:185], v[16:19]
	v_mfma_f32_16x16x32_bf16 v[28:31], v[136:139], v[182:185], v[28:31]
	v_mfma_f32_16x16x32_bf16 v[12:15], v[128:131], v[190:193], v[12:15]
	v_mfma_f32_16x16x32_bf16 v[8:11], v[136:139], v[190:193], v[8:11]
	v_mfma_f32_16x16x32_bf16 v[124:127], v[128:131], v[198:201], v[124:127]
	v_mfma_f32_16x16x32_bf16 v[120:123], v[136:139], v[198:201], v[120:123]
	v_mfma_f32_16x16x32_bf16 v[108:111], v[128:131], v[206:209], v[108:111]
	v_mfma_f32_16x16x32_bf16 v[104:107], v[136:139], v[206:209], v[104:107]
	s_add_u32 s46, s46, s26
	s_addc_u32 s47, s47, 0
	s_mov_b32 m0, s8
	v_mfma_f32_16x16x32_bf16 v[16:19], v[132:135], v[186:189], v[16:19]
	global_load_lds_dwordx4 v158, s[46:47]
	v_mfma_f32_16x16x32_bf16 v[28:31], v[140:143], v[186:189], v[28:31]
	v_mfma_f32_16x16x32_bf16 v[12:15], v[132:135], v[194:197], v[12:15]
	v_mfma_f32_16x16x32_bf16 v[8:11], v[140:143], v[194:197], v[8:11]
	v_mfma_f32_16x16x32_bf16 v[124:127], v[132:135], v[202:205], v[124:127]
	v_mfma_f32_16x16x32_bf16 v[120:123], v[140:143], v[202:205], v[120:123]
	v_mfma_f32_16x16x32_bf16 v[108:111], v[132:135], v[232:235], v[108:111]
	v_mfma_f32_16x16x32_bf16 v[104:107], v[140:143], v[232:235], v[104:107]
	s_setprio 0
	s_setprio 1
	v_mfma_f32_16x16x32_bf16 v[24:27], v[144:147], v[182:185], v[24:27]
	v_mfma_f32_16x16x32_bf16 v[20:23], v[174:177], v[182:185], v[20:23]
	v_mfma_f32_16x16x32_bf16 v[4:7], v[144:147], v[190:193], v[4:7]
	v_mfma_f32_16x16x32_bf16 v[0:3], v[174:177], v[190:193], v[0:3]
	v_mfma_f32_16x16x32_bf16 v[116:119], v[144:147], v[198:201], v[116:119]
	v_mfma_f32_16x16x32_bf16 v[112:115], v[174:177], v[198:201], v[112:115]
	v_mfma_f32_16x16x32_bf16 v[100:103], v[144:147], v[206:209], v[100:103]
	v_mfma_f32_16x16x32_bf16 v[96:99], v[174:177], v[206:209], v[96:99]
	s_mov_b32 m0, s9
	v_mfma_f32_16x16x32_bf16 v[24:27], v[148:151], v[186:189], v[24:27]
	global_load_lds_dwordx4 v162, s[46:47]
	v_mfma_f32_16x16x32_bf16 v[20:23], v[178:181], v[186:189], v[20:23]
	v_mfma_f32_16x16x32_bf16 v[4:7], v[148:151], v[194:197], v[4:7]
	v_mfma_f32_16x16x32_bf16 v[0:3], v[178:181], v[194:197], v[0:3]
	v_mfma_f32_16x16x32_bf16 v[116:119], v[148:151], v[202:205], v[116:119]
	v_mfma_f32_16x16x32_bf16 v[112:115], v[178:181], v[202:205], v[112:115]
	v_mfma_f32_16x16x32_bf16 v[100:103], v[148:151], v[232:235], v[100:103]
	v_mfma_f32_16x16x32_bf16 v[96:99], v[178:181], v[232:235], v[96:99]
	s_setprio 0
	s_barrier
	ds_read_b128 v[182:185], v230 offset:49152
	ds_read_b128 v[186:189], v230 offset:50176
	ds_read_b128 v[190:193], v230 offset:51200
	ds_read_b128 v[194:197], v230 offset:52224
	ds_read_b128 v[198:201], v230 offset:53248
	ds_read_b128 v[202:205], v230 offset:54272
	ds_read_b128 v[206:209], v230 offset:55296
	ds_read_b128 v[232:235], v230 offset:56320
	s_waitcnt vmcnt(2)
	s_waitcnt lgkmcnt(0)
	s_barrier
	s_setprio 1
	s_waitcnt lgkmcnt(0)
	v_mfma_f32_16x16x32_bf16 v[92:95], v[128:131], v[182:185], v[92:95]
	v_mfma_f32_16x16x32_bf16 v[88:91], v[136:139], v[182:185], v[88:91]
	s_add_u32 vcc_lo, s70, s6
	s_addc_u32 vcc_hi, s71, s7
	s_sub_u32 vcc_lo, vcc_lo, s26
	s_subb_u32 vcc_hi, vcc_hi, 0
	s_add_i32 m0, s3, 0x18000
	v_mfma_f32_16x16x32_bf16 v[76:79], v[128:131], v[190:193], v[76:79]
	global_load_lds_dwordx4 v160, vcc
	v_mfma_f32_16x16x32_bf16 v[72:75], v[136:139], v[190:193], v[72:75]
	v_mfma_f32_16x16x32_bf16 v[60:63], v[128:131], v[198:201], v[60:63]
	v_mfma_f32_16x16x32_bf16 v[56:59], v[136:139], v[198:201], v[56:59]
	v_mfma_f32_16x16x32_bf16 v[44:47], v[128:131], v[206:209], v[44:47]
	v_mfma_f32_16x16x32_bf16 v[40:43], v[136:139], v[206:209], v[40:43]
	s_add_i32 m0, s3, 0x1a000
	v_mfma_f32_16x16x32_bf16 v[92:95], v[132:135], v[186:189], v[92:95]
	global_load_lds_dwordx4 v164, vcc
	v_mfma_f32_16x16x32_bf16 v[88:91], v[140:143], v[186:189], v[88:91]
	v_mfma_f32_16x16x32_bf16 v[76:79], v[132:135], v[194:197], v[76:79]
	v_mfma_f32_16x16x32_bf16 v[72:75], v[140:143], v[194:197], v[72:75]
	v_mfma_f32_16x16x32_bf16 v[60:63], v[132:135], v[202:205], v[60:63]
	s_add_u32 vcc_lo, vcc_lo, s26
	s_addc_u32 vcc_hi, vcc_hi, 0
	s_add_i32 m0, s3, 0x1c000
	v_mfma_f32_16x16x32_bf16 v[56:59], v[140:143], v[202:205], v[56:59]
	global_load_lds_dwordx4 v160, vcc
	v_mfma_f32_16x16x32_bf16 v[44:47], v[132:135], v[232:235], v[44:47]
	v_mfma_f32_16x16x32_bf16 v[40:43], v[140:143], v[232:235], v[40:43]
	s_setprio 0
	s_setprio 1
	v_mfma_f32_16x16x32_bf16 v[84:87], v[144:147], v[182:185], v[84:87]
	v_mfma_f32_16x16x32_bf16 v[80:83], v[174:177], v[182:185], v[80:83]
	s_add_i32 m0, s3, 0x1e000
	v_mfma_f32_16x16x32_bf16 v[68:71], v[144:147], v[190:193], v[68:71]
	global_load_lds_dwordx4 v164, vcc
	v_mfma_f32_16x16x32_bf16 v[64:67], v[174:177], v[190:193], v[64:67]
	v_mfma_f32_16x16x32_bf16 v[52:55], v[144:147], v[198:201], v[52:55]
	v_mfma_f32_16x16x32_bf16 v[48:51], v[174:177], v[198:201], v[48:51]
	v_mfma_f32_16x16x32_bf16 v[36:39], v[144:147], v[206:209], v[36:39]
	v_mfma_f32_16x16x32_bf16 v[32:35], v[174:177], v[206:209], v[32:35]
	s_add_u32 vcc_lo, s46, s6
	s_addc_u32 vcc_hi, s47, s7
	s_sub_u32 vcc_lo, vcc_lo, s26
	s_subb_u32 vcc_hi, vcc_hi, 0
	s_mov_b32 m0, s30
	v_mfma_f32_16x16x32_bf16 v[84:87], v[148:151], v[186:189], v[84:87]
	global_load_lds_dwordx4 v158, vcc
	v_mfma_f32_16x16x32_bf16 v[80:83], v[178:181], v[186:189], v[80:83]
	v_mfma_f32_16x16x32_bf16 v[68:71], v[148:151], v[194:197], v[68:71]
	v_mfma_f32_16x16x32_bf16 v[64:67], v[178:181], v[194:197], v[64:67]
	v_mfma_f32_16x16x32_bf16 v[52:55], v[148:151], v[202:205], v[52:55]
	s_mov_b32 m0, s31
	v_mfma_f32_16x16x32_bf16 v[48:51], v[178:181], v[202:205], v[48:51]
	global_load_lds_dwordx4 v162, vcc
	v_mfma_f32_16x16x32_bf16 v[36:39], v[148:151], v[232:235], v[36:39]
	v_mfma_f32_16x16x32_bf16 v[32:35], v[178:181], v[232:235], v[32:35]
	s_setprio 0
	s_barrier
	s_add_u32 s44, s44, 0x100
	s_addc_u32 s45, s45, 0
	s_add_u32 s23, s23, 0x100
	s_addc_u32 s48, s48, 0
	s_cmp_ge_u32 s49, s88
	s_mov_b32 s46, s49
	s_cbranch_scc1 .LBB0_249
.LBB0_248:
	s_add_i32 s49, s46, 2
	s_add_u32 s69, s44, 0x80
	s_addc_u32 s47, s45, 0
	s_add_i32 s80, 0, 0x10000
	s_cmp_eq_u32 s90, s46
	s_cselect_b32 s47, s65, s47
	s_cselect_b32 s46, s64, s69
	s_cselect_b32 s71, s67, s48
	s_cselect_b32 s70, s66, s23
	s_add_i32 s69, 0, 0x14000
	ds_read_b128 v[128:131], v236
	ds_read_b128 v[132:135], v236 offset:1024
	ds_read_b128 v[136:139], v236 offset:2048
	ds_read_b128 v[140:143], v236 offset:3072
	ds_read_b128 v[144:147], v237
	ds_read_b128 v[148:151], v237 offset:1024
	ds_read_b128 v[174:177], v237 offset:2048
	ds_read_b128 v[178:181], v237 offset:3072
	ds_read_b128 v[182:185], v230
	ds_read_b128 v[186:189], v230 offset:1024
	ds_read_b128 v[190:193], v230 offset:2048
	ds_read_b128 v[194:197], v230 offset:3072
	ds_read_b128 v[198:201], v230 offset:4096
	ds_read_b128 v[202:205], v230 offset:5120
	ds_read_b128 v[206:209], v230 offset:6144
	ds_read_b128 v[232:235], v230 offset:7168
	s_waitcnt vmcnt(6)
	s_waitcnt lgkmcnt(0)
	s_barrier
	s_setprio 1
	s_waitcnt lgkmcnt(0)
	v_mfma_f32_16x16x32_bf16 v[16:19], v[128:131], v[182:185], v[16:19]
	v_mfma_f32_16x16x32_bf16 v[28:31], v[136:139], v[182:185], v[28:31]
	v_mfma_f32_16x16x32_bf16 v[12:15], v[128:131], v[190:193], v[12:15]
	v_mfma_f32_16x16x32_bf16 v[8:11], v[136:139], v[190:193], v[8:11]
	v_mfma_f32_16x16x32_bf16 v[124:127], v[128:131], v[198:201], v[124:127]
	v_mfma_f32_16x16x32_bf16 v[120:123], v[136:139], v[198:201], v[120:123]
	v_mfma_f32_16x16x32_bf16 v[108:111], v[128:131], v[206:209], v[108:111]
	v_mfma_f32_16x16x32_bf16 v[104:107], v[136:139], v[206:209], v[104:107]
	s_add_i32 m0, s50, 0xc000
	v_mfma_f32_16x16x32_bf16 v[16:19], v[132:135], v[186:189], v[16:19]
	global_load_lds_dwordx4 v170, s[44:45]
	v_mfma_f32_16x16x32_bf16 v[28:31], v[140:143], v[186:189], v[28:31]
	v_mfma_f32_16x16x32_bf16 v[12:15], v[132:135], v[194:197], v[12:15]
	v_mfma_f32_16x16x32_bf16 v[8:11], v[140:143], v[194:197], v[8:11]
	v_mfma_f32_16x16x32_bf16 v[124:127], v[132:135], v[202:205], v[124:127]
	v_mfma_f32_16x16x32_bf16 v[120:123], v[140:143], v[202:205], v[120:123]
	v_mfma_f32_16x16x32_bf16 v[108:111], v[132:135], v[232:235], v[108:111]
	v_mfma_f32_16x16x32_bf16 v[104:107], v[140:143], v[232:235], v[104:107]
	s_setprio 0
	s_setprio 1
	v_mfma_f32_16x16x32_bf16 v[24:27], v[144:147], v[182:185], v[24:27]
	v_mfma_f32_16x16x32_bf16 v[20:23], v[174:177], v[182:185], v[20:23]
	v_mfma_f32_16x16x32_bf16 v[4:7], v[144:147], v[190:193], v[4:7]
	v_mfma_f32_16x16x32_bf16 v[0:3], v[174:177], v[190:193], v[0:3]
	v_mfma_f32_16x16x32_bf16 v[116:119], v[144:147], v[198:201], v[116:119]
	v_mfma_f32_16x16x32_bf16 v[112:115], v[174:177], v[198:201], v[112:115]
	v_mfma_f32_16x16x32_bf16 v[100:103], v[144:147], v[206:209], v[100:103]
	v_mfma_f32_16x16x32_bf16 v[96:99], v[174:177], v[206:209], v[96:99]
	s_add_i32 m0, s50, 0xe000
	v_mfma_f32_16x16x32_bf16 v[24:27], v[148:151], v[186:189], v[24:27]
	global_load_lds_dwordx4 v172, s[44:45]
	v_mfma_f32_16x16x32_bf16 v[20:23], v[178:181], v[186:189], v[20:23]
	v_mfma_f32_16x16x32_bf16 v[4:7], v[148:151], v[194:197], v[4:7]
	v_mfma_f32_16x16x32_bf16 v[0:3], v[178:181], v[194:197], v[0:3]
	v_mfma_f32_16x16x32_bf16 v[116:119], v[148:151], v[202:205], v[116:119]
	v_mfma_f32_16x16x32_bf16 v[112:115], v[178:181], v[202:205], v[112:115]
	v_mfma_f32_16x16x32_bf16 v[100:103], v[148:151], v[232:235], v[100:103]
	v_mfma_f32_16x16x32_bf16 v[96:99], v[178:181], v[232:235], v[96:99]
	s_setprio 0
	s_barrier
	ds_read_b128 v[182:185], v230 offset:16384
	ds_read_b128 v[186:189], v230 offset:17408
	ds_read_b128 v[190:193], v230 offset:18432
	ds_read_b128 v[194:197], v230 offset:19456
	ds_read_b128 v[198:201], v230 offset:20480
	ds_read_b128 v[202:205], v230 offset:21504
	ds_read_b128 v[206:209], v230 offset:22528
	ds_read_b128 v[232:235], v230 offset:23552
	s_waitcnt vmcnt(2)
	s_waitcnt lgkmcnt(0)
	s_barrier
	s_setprio 1
	s_waitcnt lgkmcnt(0)
	v_mfma_f32_16x16x32_bf16 v[92:95], v[128:131], v[182:185], v[92:95]
	v_mfma_f32_16x16x32_bf16 v[88:91], v[136:139], v[182:185], v[88:91]
	s_add_i32 s80, s80, s3
	s_mov_b32 m0, s80
	v_mfma_f32_16x16x32_bf16 v[76:79], v[128:131], v[190:193], v[76:79]
	global_load_lds_dwordx4 v160, s[70:71]
	v_mfma_f32_16x16x32_bf16 v[72:75], v[136:139], v[190:193], v[72:75]
	v_mfma_f32_16x16x32_bf16 v[60:63], v[128:131], v[198:201], v[60:63]
	v_mfma_f32_16x16x32_bf16 v[56:59], v[136:139], v[198:201], v[56:59]
	v_mfma_f32_16x16x32_bf16 v[44:47], v[128:131], v[206:209], v[44:47]
	v_mfma_f32_16x16x32_bf16 v[40:43], v[136:139], v[206:209], v[40:43]
	s_add_i32 m0, s80, 0x2000
	s_add_i32 s69, s69, s3
	v_mfma_f32_16x16x32_bf16 v[92:95], v[132:135], v[186:189], v[92:95]
	global_load_lds_dwordx4 v164, s[70:71]
	v_mfma_f32_16x16x32_bf16 v[88:91], v[140:143], v[186:189], v[88:91]
	v_mfma_f32_16x16x32_bf16 v[76:79], v[132:135], v[194:197], v[76:79]
	v_mfma_f32_16x16x32_bf16 v[72:75], v[140:143], v[194:197], v[72:75]
	v_mfma_f32_16x16x32_bf16 v[60:63], v[132:135], v[202:205], v[60:63]
	s_add_u32 s70, s70, s26
	s_addc_u32 s71, s71, 0
	s_mov_b32 m0, s69
	v_mfma_f32_16x16x32_bf16 v[56:59], v[140:143], v[202:205], v[56:59]
	global_load_lds_dwordx4 v160, s[70:71]
	v_mfma_f32_16x16x32_bf16 v[44:47], v[132:135], v[232:235], v[44:47]
	v_mfma_f32_16x16x32_bf16 v[40:43], v[140:143], v[232:235], v[40:43]
	s_setprio 0
	s_setprio 1
	v_mfma_f32_16x16x32_bf16 v[84:87], v[144:147], v[182:185], v[84:87]
	v_mfma_f32_16x16x32_bf16 v[80:83], v[174:177], v[182:185], v[80:83]
	s_add_i32 m0, s69, 0x2000
	v_mfma_f32_16x16x32_bf16 v[68:71], v[144:147], v[190:193], v[68:71]
	global_load_lds_dwordx4 v164, s[70:71]
	v_mfma_f32_16x16x32_bf16 v[64:67], v[174:177], v[190:193], v[64:67]
	v_mfma_f32_16x16x32_bf16 v[52:55], v[144:147], v[198:201], v[52:55]
	v_mfma_f32_16x16x32_bf16 v[48:51], v[174:177], v[198:201], v[48:51]
	v_mfma_f32_16x16x32_bf16 v[36:39], v[144:147], v[206:209], v[36:39]
	v_mfma_f32_16x16x32_bf16 v[32:35], v[174:177], v[206:209], v[32:35]
	s_mov_b32 m0, s50
	v_mfma_f32_16x16x32_bf16 v[84:87], v[148:151], v[186:189], v[84:87]
	global_load_lds_dwordx4 v158, s[46:47]
	v_mfma_f32_16x16x32_bf16 v[80:83], v[178:181], v[186:189], v[80:83]
	v_mfma_f32_16x16x32_bf16 v[68:71], v[148:151], v[194:197], v[68:71]
	v_mfma_f32_16x16x32_bf16 v[64:67], v[178:181], v[194:197], v[64:67]
	v_mfma_f32_16x16x32_bf16 v[52:55], v[148:151], v[202:205], v[52:55]
	s_mov_b32 m0, s51
	v_mfma_f32_16x16x32_bf16 v[48:51], v[178:181], v[202:205], v[48:51]
	global_load_lds_dwordx4 v162, s[46:47]
	v_mfma_f32_16x16x32_bf16 v[36:39], v[148:151], v[232:235], v[36:39]
	v_mfma_f32_16x16x32_bf16 v[32:35], v[178:181], v[232:235], v[32:35]
	s_setprio 0
	s_barrier
	ds_read_b128 v[128:131], v238
	ds_read_b128 v[132:135], v238 offset:1024
	ds_read_b128 v[136:139], v238 offset:2048
	ds_read_b128 v[140:143], v238 offset:3072
	ds_read_b128 v[144:147], v239
	ds_read_b128 v[148:151], v239 offset:1024
	ds_read_b128 v[174:177], v239 offset:2048
	ds_read_b128 v[178:181], v239 offset:3072
	ds_read_b128 v[182:185], v230 offset:32768
	ds_read_b128 v[186:189], v230 offset:33792
	ds_read_b128 v[190:193], v230 offset:34816
	ds_read_b128 v[194:197], v230 offset:35840
	ds_read_b128 v[198:201], v230 offset:36864
	ds_read_b128 v[202:205], v230 offset:37888
	ds_read_b128 v[206:209], v230 offset:38912
	ds_read_b128 v[232:235], v230 offset:39936
	s_waitcnt vmcnt(6)
	s_waitcnt lgkmcnt(0)
	s_barrier
	s_setprio 1
	s_waitcnt lgkmcnt(0)
	v_mfma_f32_16x16x32_bf16 v[16:19], v[128:131], v[182:185], v[16:19]
	v_mfma_f32_16x16x32_bf16 v[28:31], v[136:139], v[182:185], v[28:31]
	v_mfma_f32_16x16x32_bf16 v[12:15], v[128:131], v[190:193], v[12:15]
	v_mfma_f32_16x16x32_bf16 v[8:11], v[136:139], v[190:193], v[8:11]
	v_mfma_f32_16x16x32_bf16 v[124:127], v[128:131], v[198:201], v[124:127]
	v_mfma_f32_16x16x32_bf16 v[120:123], v[136:139], v[198:201], v[120:123]
	v_mfma_f32_16x16x32_bf16 v[108:111], v[128:131], v[206:209], v[108:111]
	v_mfma_f32_16x16x32_bf16 v[104:107], v[136:139], v[206:209], v[104:107]
	s_add_u32 s46, s46, s26
	s_addc_u32 s47, s47, 0
	s_mov_b32 m0, s8
	v_mfma_f32_16x16x32_bf16 v[16:19], v[132:135], v[186:189], v[16:19]
	global_load_lds_dwordx4 v158, s[46:47]
	v_mfma_f32_16x16x32_bf16 v[28:31], v[140:143], v[186:189], v[28:31]
	v_mfma_f32_16x16x32_bf16 v[12:15], v[132:135], v[194:197], v[12:15]
	v_mfma_f32_16x16x32_bf16 v[8:11], v[140:143], v[194:197], v[8:11]
	v_mfma_f32_16x16x32_bf16 v[124:127], v[132:135], v[202:205], v[124:127]
	v_mfma_f32_16x16x32_bf16 v[120:123], v[140:143], v[202:205], v[120:123]
	v_mfma_f32_16x16x32_bf16 v[108:111], v[132:135], v[232:235], v[108:111]
	v_mfma_f32_16x16x32_bf16 v[104:107], v[140:143], v[232:235], v[104:107]
	s_setprio 0
	s_setprio 1
	v_mfma_f32_16x16x32_bf16 v[24:27], v[144:147], v[182:185], v[24:27]
	v_mfma_f32_16x16x32_bf16 v[20:23], v[174:177], v[182:185], v[20:23]
	v_mfma_f32_16x16x32_bf16 v[4:7], v[144:147], v[190:193], v[4:7]
	v_mfma_f32_16x16x32_bf16 v[0:3], v[174:177], v[190:193], v[0:3]
	v_mfma_f32_16x16x32_bf16 v[116:119], v[144:147], v[198:201], v[116:119]
	v_mfma_f32_16x16x32_bf16 v[112:115], v[174:177], v[198:201], v[112:115]
	v_mfma_f32_16x16x32_bf16 v[100:103], v[144:147], v[206:209], v[100:103]
	v_mfma_f32_16x16x32_bf16 v[96:99], v[174:177], v[206:209], v[96:99]
	s_mov_b32 m0, s9
	v_mfma_f32_16x16x32_bf16 v[24:27], v[148:151], v[186:189], v[24:27]
	global_load_lds_dwordx4 v162, s[46:47]
	v_mfma_f32_16x16x32_bf16 v[20:23], v[178:181], v[186:189], v[20:23]
	v_mfma_f32_16x16x32_bf16 v[4:7], v[148:151], v[194:197], v[4:7]
	v_mfma_f32_16x16x32_bf16 v[0:3], v[178:181], v[194:197], v[0:3]
	v_mfma_f32_16x16x32_bf16 v[116:119], v[148:151], v[202:205], v[116:119]
	v_mfma_f32_16x16x32_bf16 v[112:115], v[178:181], v[202:205], v[112:115]
	v_mfma_f32_16x16x32_bf16 v[100:103], v[148:151], v[232:235], v[100:103]
	v_mfma_f32_16x16x32_bf16 v[96:99], v[178:181], v[232:235], v[96:99]
	s_setprio 0
	s_barrier
	ds_read_b128 v[182:185], v230 offset:49152
	ds_read_b128 v[186:189], v230 offset:50176
	ds_read_b128 v[190:193], v230 offset:51200
	ds_read_b128 v[194:197], v230 offset:52224
	ds_read_b128 v[198:201], v230 offset:53248
	ds_read_b128 v[202:205], v230 offset:54272
	ds_read_b128 v[206:209], v230 offset:55296
	ds_read_b128 v[232:235], v230 offset:56320
	s_waitcnt vmcnt(2)
	s_waitcnt lgkmcnt(0)
	s_barrier
	s_setprio 1
	s_waitcnt lgkmcnt(0)
	v_mfma_f32_16x16x32_bf16 v[92:95], v[128:131], v[182:185], v[92:95]
	v_mfma_f32_16x16x32_bf16 v[88:91], v[136:139], v[182:185], v[88:91]
	s_add_u32 vcc_lo, s70, s6
	s_addc_u32 vcc_hi, s71, s7
	s_sub_u32 vcc_lo, vcc_lo, s26
	s_subb_u32 vcc_hi, vcc_hi, 0
	s_add_i32 m0, s3, 0x18000
	v_mfma_f32_16x16x32_bf16 v[76:79], v[128:131], v[190:193], v[76:79]
	global_load_lds_dwordx4 v160, vcc
	v_mfma_f32_16x16x32_bf16 v[72:75], v[136:139], v[190:193], v[72:75]
	v_mfma_f32_16x16x32_bf16 v[60:63], v[128:131], v[198:201], v[60:63]
	v_mfma_f32_16x16x32_bf16 v[56:59], v[136:139], v[198:201], v[56:59]
	v_mfma_f32_16x16x32_bf16 v[44:47], v[128:131], v[206:209], v[44:47]
	v_mfma_f32_16x16x32_bf16 v[40:43], v[136:139], v[206:209], v[40:43]
	s_add_i32 m0, s3, 0x1a000
	v_mfma_f32_16x16x32_bf16 v[92:95], v[132:135], v[186:189], v[92:95]
	global_load_lds_dwordx4 v164, vcc
	v_mfma_f32_16x16x32_bf16 v[88:91], v[140:143], v[186:189], v[88:91]
	v_mfma_f32_16x16x32_bf16 v[76:79], v[132:135], v[194:197], v[76:79]
	v_mfma_f32_16x16x32_bf16 v[72:75], v[140:143], v[194:197], v[72:75]
	v_mfma_f32_16x16x32_bf16 v[60:63], v[132:135], v[202:205], v[60:63]
	s_add_u32 vcc_lo, vcc_lo, s26
	s_addc_u32 vcc_hi, vcc_hi, 0
	s_add_i32 m0, s3, 0x1c000
	v_mfma_f32_16x16x32_bf16 v[56:59], v[140:143], v[202:205], v[56:59]
	global_load_lds_dwordx4 v160, vcc
	v_mfma_f32_16x16x32_bf16 v[44:47], v[132:135], v[232:235], v[44:47]
	v_mfma_f32_16x16x32_bf16 v[40:43], v[140:143], v[232:235], v[40:43]
	s_setprio 0
	s_setprio 1
	v_mfma_f32_16x16x32_bf16 v[84:87], v[144:147], v[182:185], v[84:87]
	v_mfma_f32_16x16x32_bf16 v[80:83], v[174:177], v[182:185], v[80:83]
	s_add_i32 m0, s3, 0x1e000
	v_mfma_f32_16x16x32_bf16 v[68:71], v[144:147], v[190:193], v[68:71]
	global_load_lds_dwordx4 v164, vcc
	v_mfma_f32_16x16x32_bf16 v[64:67], v[174:177], v[190:193], v[64:67]
	v_mfma_f32_16x16x32_bf16 v[52:55], v[144:147], v[198:201], v[52:55]
	v_mfma_f32_16x16x32_bf16 v[48:51], v[174:177], v[198:201], v[48:51]
	v_mfma_f32_16x16x32_bf16 v[36:39], v[144:147], v[206:209], v[36:39]
	v_mfma_f32_16x16x32_bf16 v[32:35], v[174:177], v[206:209], v[32:35]
	s_add_u32 vcc_lo, s46, s6
	s_addc_u32 vcc_hi, s47, s7
	s_sub_u32 vcc_lo, vcc_lo, s26
	s_subb_u32 vcc_hi, vcc_hi, 0
	s_mov_b32 m0, s30
	v_mfma_f32_16x16x32_bf16 v[84:87], v[148:151], v[186:189], v[84:87]
	global_load_lds_dwordx4 v158, vcc
	v_mfma_f32_16x16x32_bf16 v[80:83], v[178:181], v[186:189], v[80:83]
	v_mfma_f32_16x16x32_bf16 v[68:71], v[148:151], v[194:197], v[68:71]
	v_mfma_f32_16x16x32_bf16 v[64:67], v[178:181], v[194:197], v[64:67]
	v_mfma_f32_16x16x32_bf16 v[52:55], v[148:151], v[202:205], v[52:55]
	s_mov_b32 m0, s31
	v_mfma_f32_16x16x32_bf16 v[48:51], v[178:181], v[202:205], v[48:51]
	global_load_lds_dwordx4 v162, vcc
	v_mfma_f32_16x16x32_bf16 v[36:39], v[148:151], v[232:235], v[36:39]
	v_mfma_f32_16x16x32_bf16 v[32:35], v[178:181], v[232:235], v[32:35]
	s_setprio 0
	s_barrier
	s_add_u32 s44, s44, 0x100
	s_addc_u32 s45, s45, 0
	s_add_u32 s23, s23, 0x100
	s_addc_u32 s48, s48, 0
	s_cmp_ge_u32 s49, s88
	s_mov_b32 s46, s49
	s_cbranch_scc0 .LBB0_248
